# ssm pass 3: a wave's second unit takes the mirrored chunk index so every wave carries the same total chain length
# speedup vs baseline: 1.0078x; 1.0055x over previous
; __device__ __forceinline__ void ssm_pass3h(CArgs* ap, const float* COEF, int l, const bf16_t* PROJ, const float* SST, bf16_t* YS, LAS unsigned char* wlds, int unit, int lane) {
;     ...
;         for (int q = 0; q < 4; ++q) {
;             const int t = 16 * blk + 4 * q;
;             u32x4 wc[8];
; #pragma unroll
;             for (int j = 0; j < 8; ++j) wc[j] = wn[j];
;             const int tn = (t + 4 < 128) ? t + 4 : t;
; #pragma unroll
;             for (int tt = 0; tt < 4; ++tt) { wn[2 * tt] = ((const u32x4*)(up + (size_t)(tn + tt) * INW))[0]; wn[2 * tt + 1] = ((const u32x4*)(up + (size_t)(tn + tt) * INW))[1]; }
; #pragma unroll
;             for (int tt = 0; tt < 4; ++tt) {
;                 const u32x4 w0 = wc[2 * tt], w1 = wc[2 * tt + 1];
;                 const unsigned u2[8] = {w0.x, w0.y, w0.z, w0.w, w1.x, w1.y, w1.z, w1.w};
;                 float br_ = 0.f, bi_ = 0.f;
; #pragma unroll
;                 for (int k = 0; k < 8; ++k) { br_ = __builtin_amdgcn_fdot2_f32_bf16(__builtin_bit_cast(bf16x2v, bbr2[k]), __builtin_bit_cast(bf16x2v, u2[k]), br_, false);
;                                                bi_ = __builtin_amdgcn_fdot2_f32_bf16(__builtin_bit_cast(bf16x2v, bbi2[k]), __builtin_bit_cast(bf16x2v, u2[k]), bi_, false); }
;                 const float nr = abr * hr - abi * hi + br_, ni = abr * hi + abi * hr + bi_; hr = nr; hi = ni;
;                 Hf[(4 * q + tt) * 132 + lane] = hr; Hf[(4 * q + tt) * 132 + 64 + lane] = hi;
;             }
.LBB0_150:
	s_add_i32 s13, s14, 4
	s_add_i32 s78, s14, 16
	s_cmpk_lt_u32 s14, 0x70
	s_cselect_b32 s78, s78, s14
	s_mul_i32 s78, s78, 0x2400
	s_lshl_b64 s[14:15], s[78:79], 1
	s_add_u32 s14, s2, s14
	s_addc_u32 s15, s3, s15
	s_waitcnt vmcnt(14)
	v_mfma_f32_4x4x4_16b_bf16 v[144:147], v[24:25], v[208:209], 0
	v_mfma_f32_4x4x4_16b_bf16 v[148:151], v[24:25], v[210:211], 0
	s_nop 0
	v_mfma_f32_4x4x4_16b_bf16 v[144:147], v[26:27], v[212:213], v[144:147]
	v_mfma_f32_4x4x4_16b_bf16 v[148:151], v[26:27], v[214:215], v[148:151]
	s_nop 0
	v_mfma_f32_4x4x4_16b_bf16 v[144:147], v[20:21], v[216:217], v[144:147]
	v_mfma_f32_4x4x4_16b_bf16 v[148:151], v[20:21], v[218:219], v[148:151]
	s_nop 0
	v_mfma_f32_4x4x4_16b_bf16 v[144:147], v[22:23], v[220:221], v[144:147]
	v_mfma_f32_4x4x4_16b_bf16 v[148:151], v[22:23], v[222:223], v[148:151]
	s_nop 0
	global_load_dwordx4 v[20:23], v224, s[14:15] offset:16
	global_load_dwordx4 v[24:27], v224, s[14:15]
	v_add_u32_e32 v97, s12, v99
	v_add_u32_e32 v184, 32, v97
	v_add_u32_e32 v185, 48, v97
	v_fma_f32 v152, -v3, v91, v144
	v_fma_f32 v153, v3, v90, v148
	v_fma_f32 v90, v2, v90, v152
	v_fma_f32 v91, v2, v91, v153
	ds_write2st64_b32 v97, v90, v91 offset1:1
	v_fma_f32 v152, -v3, v91, v145
	v_fma_f32 v153, v3, v90, v149
	v_fma_f32 v90, v2, v90, v152
	v_fma_f32 v91, v2, v91, v153
	ds_write2_b32 v97, v90, v91 offset0:132 offset1:196
	v_fma_f32 v152, -v3, v91, v146
	v_fma_f32 v153, v3, v90, v150
	v_fma_f32 v90, v2, v90, v152
	v_fma_f32 v91, v2, v91, v153
	ds_write2st64_b32 v184, v90, v91 offset0:4 offset1:5
	v_fma_f32 v152, -v3, v91, v147
	v_fma_f32 v153, v3, v90, v151
	v_fma_f32 v90, v2, v90, v152
	v_fma_f32 v91, v2, v91, v153
	ds_write2st64_b32 v185, v90, v91 offset0:6 offset1:7
	s_addk_i32 s12, 0x840
	s_mov_b32 s14, s13
	s_add_i32 s13, s14, 4
	s_add_i32 s78, s14, 16
	s_cmpk_lt_u32 s14, 0x70
	s_cselect_b32 s78, s78, s14
	s_mul_i32 s78, s78, 0x2400
	s_lshl_b64 s[14:15], s[78:79], 1
	s_add_u32 s14, s2, s14
	s_addc_u32 s15, s3, s15
	s_waitcnt vmcnt(14)
	v_mfma_f32_4x4x4_16b_bf16 v[144:147], v[32:33], v[208:209], 0
	v_mfma_f32_4x4x4_16b_bf16 v[148:151], v[32:33], v[210:211], 0
	s_nop 0
	v_mfma_f32_4x4x4_16b_bf16 v[144:147], v[34:35], v[212:213], v[144:147]
	v_mfma_f32_4x4x4_16b_bf16 v[148:151], v[34:35], v[214:215], v[148:151]
	s_nop 0
	v_mfma_f32_4x4x4_16b_bf16 v[144:147], v[28:29], v[216:217], v[144:147]
	v_mfma_f32_4x4x4_16b_bf16 v[148:151], v[28:29], v[218:219], v[148:151]
	s_nop 0
	v_mfma_f32_4x4x4_16b_bf16 v[144:147], v[30:31], v[220:221], v[144:147]
	v_mfma_f32_4x4x4_16b_bf16 v[148:151], v[30:31], v[222:223], v[148:151]
	s_nop 0
	global_load_dwordx4 v[28:31], v224, s[14:15] offset:16
	global_load_dwordx4 v[32:35], v224, s[14:15]
	v_add_u32_e32 v97, s12, v99
	v_add_u32_e32 v184, 32, v97
	v_add_u32_e32 v185, 48, v97
	v_fma_f32 v152, -v3, v91, v144
	v_fma_f32 v153, v3, v90, v148
	v_fma_f32 v90, v2, v90, v152
	v_fma_f32 v91, v2, v91, v153
	ds_write2st64_b32 v97, v90, v91 offset1:1
	v_fma_f32 v152, -v3, v91, v145
	v_fma_f32 v153, v3, v90, v149
	v_fma_f32 v90, v2, v90, v152
	v_fma_f32 v91, v2, v91, v153
	ds_write2_b32 v97, v90, v91 offset0:132 offset1:196
	v_fma_f32 v152, -v3, v91, v146
	v_fma_f32 v153, v3, v90, v150
	v_fma_f32 v90, v2, v90, v152
	v_fma_f32 v91, v2, v91, v153
	ds_write2st64_b32 v184, v90, v91 offset0:4 offset1:5
	v_fma_f32 v152, -v3, v91, v147
	v_fma_f32 v153, v3, v90, v151
	v_fma_f32 v90, v2, v90, v152
	v_fma_f32 v91, v2, v91, v153
	ds_write2st64_b32 v185, v90, v91 offset0:6 offset1:7
	s_addk_i32 s12, 0x840
	s_mov_b32 s14, s13
	s_add_i32 s13, s14, 4
	s_add_i32 s78, s14, 16
	s_cmpk_lt_u32 s14, 0x70
	s_cselect_b32 s78, s78, s14
	s_mul_i32 s78, s78, 0x2400
	s_lshl_b64 s[14:15], s[78:79], 1
	s_add_u32 s14, s2, s14
	s_addc_u32 s15, s3, s15
	s_waitcnt vmcnt(14)
	v_mfma_f32_4x4x4_16b_bf16 v[144:147], v[40:41], v[208:209], 0
	v_mfma_f32_4x4x4_16b_bf16 v[148:151], v[40:41], v[210:211], 0
	s_nop 0
	v_mfma_f32_4x4x4_16b_bf16 v[144:147], v[42:43], v[212:213], v[144:147]
	v_mfma_f32_4x4x4_16b_bf16 v[148:151], v[42:43], v[214:215], v[148:151]
	s_nop 0
	v_mfma_f32_4x4x4_16b_bf16 v[144:147], v[36:37], v[216:217], v[144:147]
	v_mfma_f32_4x4x4_16b_bf16 v[148:151], v[36:37], v[218:219], v[148:151]
	s_nop 0
	v_mfma_f32_4x4x4_16b_bf16 v[144:147], v[38:39], v[220:221], v[144:147]
	v_mfma_f32_4x4x4_16b_bf16 v[148:151], v[38:39], v[222:223], v[148:151]
	s_nop 0
	global_load_dwordx4 v[36:39], v224, s[14:15] offset:16
	global_load_dwordx4 v[40:43], v224, s[14:15]
	v_add_u32_e32 v97, s12, v99
	v_add_u32_e32 v184, 32, v97
	v_add_u32_e32 v185, 48, v97
	v_fma_f32 v152, -v3, v91, v144
	v_fma_f32 v153, v3, v90, v148
	v_fma_f32 v90, v2, v90, v152
	v_fma_f32 v91, v2, v91, v153
	ds_write2st64_b32 v97, v90, v91 offset1:1
	v_fma_f32 v152, -v3, v91, v145
	v_fma_f32 v153, v3, v90, v149
	v_fma_f32 v90, v2, v90, v152
	v_fma_f32 v91, v2, v91, v153
	ds_write2_b32 v97, v90, v91 offset0:132 offset1:196
	v_fma_f32 v152, -v3, v91, v146
	v_fma_f32 v153, v3, v90, v150
	v_fma_f32 v90, v2, v90, v152
	v_fma_f32 v91, v2, v91, v153
	ds_write2st64_b32 v184, v90, v91 offset0:4 offset1:5
	v_fma_f32 v152, -v3, v91, v147
	v_fma_f32 v153, v3, v90, v151
	v_fma_f32 v90, v2, v90, v152
	v_fma_f32 v91, v2, v91, v153
	ds_write2st64_b32 v185, v90, v91 offset0:6 offset1:7
	s_addk_i32 s12, 0x840
	s_mov_b32 s14, s13
	s_add_i32 s13, s14, 4
	s_add_i32 s78, s14, 16
	s_cmpk_lt_u32 s14, 0x70
	s_cselect_b32 s78, s78, s14
	s_mul_i32 s78, s78, 0x2400
	s_lshl_b64 s[14:15], s[78:79], 1
	s_add_u32 s14, s2, s14
	s_addc_u32 s15, s3, s15
	s_waitcnt vmcnt(14)
; __device__ __forceinline__ float gelu_t(float x) { const float p = __builtin_fmaf(x * x, -0.10294324f, -2.30220819f); return x * __builtin_amdgcn_rcpf(1.f + __builtin_amdgcn_exp2f(x * p)); }
; #define LAS __attribute__((address_space(3)))
; __device__ __forceinline__ unsigned f2bf(float f) { unsigned u = __builtin_bit_cast(unsigned, f); return (u + 0x7fffu + ((u >> 16) & 1u)) >> 16; }
; __device__ __forceinline__ void ssm_pass3h(CArgs* ap, const float* COEF, int l, const bf16_t* PROJ, const float* SST, bf16_t* YS, LAS unsigned char* wlds, int unit, int lane) {
;     ...
;                 const float nr = abr * hr - abi * hi + br_, ni = abr * hi + abi * hr + bi_; hr = nr; hi = ni;
;                 Hf[(4 * q + tt) * 132 + lane] = hr; Hf[(4 * q + tt) * 132 + 64 + lane] = hi;
;             }
;         }
;         asm volatile("s_waitcnt lgkmcnt(0)" ::: "memory");
;         f32x4 y = (f32x4){0.f, 0.f, 0.f, 0.f};
; #pragma unroll
;         for (int j = 0; j < 8; ++j) {
;             const f32x4 a4 = *(const LAS f32x4*)(Hf + fr * 132 + 16 * j + 4 * fq);
; #pragma unroll
;             for (int r = 0; r < 4; ++r) y = __builtin_amdgcn_mfma_f32_16x16x4f32(a4[r], cmB[4 * j + r], y, 0, 0, 0);
;         }
;         asm volatile("s_waitcnt lgkmcnt(0)" ::: "memory");
; #pragma unroll
;         for (int i = 0; i < 4; ++i) {
;             const size_t row = row0 + 16 * blk + 4 * fq + i;
;             YS[row * 512 + g * 16 + fr] = (bf16_t)f2bf(gelu_t(y[i] + dsk * __uint_as_float(((unsigned)uq[i]) << 16)));
;         }
; __global__ void __launch_bounds__(NTHR, 2) fwd(Args a) {
;     ...
;             else if (sp == 3) { for (int u = gw; u < 4096; u += NGW) ssm_pass3h(ap, COEF, l, PROJ, SST, YS, lds + wave * 8448, u, lane); }
	v_mfma_f32_4x4x4_16b_bf16 v[144:147], v[48:49], v[208:209], 0
	v_mfma_f32_4x4x4_16b_bf16 v[148:151], v[48:49], v[210:211], 0
	s_nop 0
	v_mfma_f32_4x4x4_16b_bf16 v[144:147], v[50:51], v[212:213], v[144:147]
	v_mfma_f32_4x4x4_16b_bf16 v[148:151], v[50:51], v[214:215], v[148:151]
	s_nop 0
	v_mfma_f32_4x4x4_16b_bf16 v[144:147], v[44:45], v[216:217], v[144:147]
	v_mfma_f32_4x4x4_16b_bf16 v[148:151], v[44:45], v[218:219], v[148:151]
	s_nop 0
	v_mfma_f32_4x4x4_16b_bf16 v[144:147], v[46:47], v[220:221], v[144:147]
	v_mfma_f32_4x4x4_16b_bf16 v[148:151], v[46:47], v[222:223], v[148:151]
	s_nop 0
	global_load_dwordx4 v[44:47], v224, s[14:15] offset:16
	global_load_dwordx4 v[48:51], v224, s[14:15]
	v_add_u32_e32 v97, s12, v99
	v_add_u32_e32 v184, 32, v97
	v_add_u32_e32 v185, 48, v97
	v_fma_f32 v152, -v3, v91, v144
	v_fma_f32 v153, v3, v90, v148
	v_fma_f32 v90, v2, v90, v152
	v_fma_f32 v91, v2, v91, v153
	ds_write2st64_b32 v97, v90, v91 offset1:1
	v_fma_f32 v152, -v3, v91, v145
	v_fma_f32 v153, v3, v90, v149
	v_fma_f32 v90, v2, v90, v152
	v_fma_f32 v91, v2, v91, v153
	ds_write2_b32 v97, v90, v91 offset0:132 offset1:196
	v_fma_f32 v152, -v3, v91, v146
	v_fma_f32 v153, v3, v90, v150
	v_fma_f32 v90, v2, v90, v152
	v_fma_f32 v91, v2, v91, v153
	ds_write2st64_b32 v184, v90, v91 offset0:4 offset1:5
	v_fma_f32 v152, -v3, v91, v147
	v_fma_f32 v153, v3, v90, v151
	v_fma_f32 v90, v2, v90, v152
	v_fma_f32 v91, v2, v91, v153
	ds_write2st64_b32 v185, v90, v91 offset0:6 offset1:7
	s_addk_i32 s12, 0x840
	s_mov_b32 s14, s13
	s_waitcnt lgkmcnt(0)
	ds_read_b128 v[144:147], v100
	ds_read_b128 v[148:151], v100 offset:64
	ds_read_b128 v[152:155], v100 offset:128
	ds_read_b128 v[168:171], v100 offset:192
	ds_read_b128 v[172:175], v100 offset:256
	ds_read_b128 v[176:179], v100 offset:320
	ds_read_b128 v[180:183], v100 offset:384
	ds_read_b128 v[184:187], v100 offset:448
	s_waitcnt vmcnt(11)
	v_lshlrev_b32_e32 v57, 16, v135
	v_mov_b32_e32 v97, v1
	v_or_b32_e32 v0, 1, v96
	v_or_b32_e32 v58, 2, v96
	v_mov_b32_e32 v59, v1
	v_or_b32_e32 v56, 3, v96
	s_add_i32 s11, s11, 1
	s_add_i32 s10, s10, 16
	s_cmp_eq_u32 s11, 8
	v_lshl_add_u64 v[60:61], v[96:97], 0, s[0:1]
	v_lshlrev_b64 v[60:61], 10, v[60:61]
	v_lshl_add_u64 v[60:61], v[92:93], 0, v[60:61]
	s_waitcnt lgkmcnt(6)
	v_mfma_f32_16x16x4_f32 v[52:55], v144, v4, 0
	v_mfma_f32_16x16x4_f32 v[188:191], v148, v8, 0
	v_mfma_f32_16x16x4_f32 v[52:55], v145, v5, v[52:55]
	v_mfma_f32_16x16x4_f32 v[188:191], v149, v9, v[188:191]
	v_mfma_f32_16x16x4_f32 v[52:55], v146, v6, v[52:55]
	v_mfma_f32_16x16x4_f32 v[188:191], v150, v10, v[188:191]
	v_mfma_f32_16x16x4_f32 v[52:55], v147, v7, v[52:55]
	v_mfma_f32_16x16x4_f32 v[188:191], v151, v11, v[188:191]
	s_waitcnt lgkmcnt(4)
	v_mfma_f32_16x16x4_f32 v[52:55], v152, v12, v[52:55]
	v_mfma_f32_16x16x4_f32 v[188:191], v168, v16, v[188:191]
	v_mfma_f32_16x16x4_f32 v[52:55], v153, v13, v[52:55]
	v_mfma_f32_16x16x4_f32 v[188:191], v169, v17, v[188:191]
	v_mfma_f32_16x16x4_f32 v[52:55], v154, v14, v[52:55]
	v_mfma_f32_16x16x4_f32 v[188:191], v170, v18, v[188:191]
	v_mfma_f32_16x16x4_f32 v[52:55], v155, v15, v[52:55]
	v_mfma_f32_16x16x4_f32 v[188:191], v171, v19, v[188:191]
	s_waitcnt lgkmcnt(2)
	v_mfma_f32_16x16x4_f32 v[52:55], v172, v89, v[52:55]
	v_mfma_f32_16x16x4_f32 v[188:191], v176, v120, v[188:191]
	v_mfma_f32_16x16x4_f32 v[52:55], v173, v117, v[52:55]
	v_mfma_f32_16x16x4_f32 v[188:191], v177, v121, v[188:191]
	v_mfma_f32_16x16x4_f32 v[52:55], v174, v118, v[52:55]
	v_mfma_f32_16x16x4_f32 v[188:191], v178, v122, v[188:191]
	v_mfma_f32_16x16x4_f32 v[52:55], v175, v119, v[52:55]
	v_mfma_f32_16x16x4_f32 v[188:191], v179, v123, v[188:191]
	s_waitcnt lgkmcnt(0)
	v_mfma_f32_16x16x4_f32 v[52:55], v180, v124, v[52:55]
	v_mfma_f32_16x16x4_f32 v[188:191], v184, v128, v[188:191]
	v_mfma_f32_16x16x4_f32 v[52:55], v181, v125, v[52:55]
	v_mfma_f32_16x16x4_f32 v[188:191], v185, v129, v[188:191]
	v_mfma_f32_16x16x4_f32 v[52:55], v182, v126, v[52:55]
	v_mfma_f32_16x16x4_f32 v[188:191], v186, v130, v[188:191]
	v_mfma_f32_16x16x4_f32 v[52:55], v183, v127, v[52:55]
	v_mfma_f32_16x16x4_f32 v[188:191], v187, v131, v[188:191]
	s_nop 9
	s_nop 1
	v_add_f32_e32 v52, v52, v188
	v_add_f32_e32 v53, v53, v189
	v_add_f32_e32 v54, v54, v190
	v_add_f32_e32 v55, v55, v191
	v_fma_f32 v52, v87, v57, v52
	v_mul_f32_e32 v57, v52, v52
	v_fmamk_f32 v57, v57, 0xbdd2d3e8, v196
	v_mul_f32_e32 v57, v52, v57
	v_exp_f32_e32 v57, v57
	s_nop 0
	v_add_f32_e32 v57, 1.0, v57
	v_rcp_f32_e32 v57, v57
	s_nop 0
	v_mul_f32_e32 v52, v52, v57
	v_bfe_u32 v57, v52, 16, 1
	v_add3_u32 v52, v52, v57, s80
	global_store_short_d16_hi v[60:61], v52, off
	v_lshl_add_u64 v[60:61], v[0:1], 0, s[0:1]
	s_waitcnt vmcnt(11)
	v_lshlrev_b32_e32 v0, 16, v134
	v_fma_f32 v0, v87, v0, v53
	v_mul_f32_e32 v52, v0, v0
	v_fmamk_f32 v52, v52, 0xbdd2d3e8, v196
	v_mul_f32_e32 v52, v0, v52
	v_exp_f32_e32 v52, v52
	v_mov_b32_e32 v57, v1
	v_add_f32_e32 v52, 1.0, v52
	v_rcp_f32_e32 v52, v52
	s_nop 0
	v_mul_f32_e32 v0, v0, v52
	v_bfe_u32 v52, v0, 16, 1
	v_add3_u32 v0, v0, v52, s80
	v_lshlrev_b64 v[52:53], 10, v[60:61]
	v_lshl_add_u64 v[52:53], v[92:93], 0, v[52:53]
	global_store_short_d16_hi v[52:53], v0, off
	s_waitcnt vmcnt(11)
	v_lshlrev_b32_e32 v0, 16, v133
	v_fma_f32 v0, v87, v0, v54
	v_mul_f32_e32 v54, v0, v0
	v_fmamk_f32 v54, v54, 0xbdd2d3e8, v196
	v_mul_f32_e32 v54, v0, v54
	v_exp_f32_e32 v54, v54
	v_lshl_add_u64 v[52:53], v[58:59], 0, s[0:1]
	v_lshlrev_b64 v[52:53], 10, v[52:53]
	v_lshl_add_u64 v[52:53], v[92:93], 0, v[52:53]
	v_add_f32_e32 v54, 1.0, v54
	v_rcp_f32_e32 v54, v54
	s_nop 0
	v_mul_f32_e32 v0, v0, v54
	v_bfe_u32 v54, v0, 16, 1
	v_add3_u32 v0, v0, v54, s80
	global_store_short_d16_hi v[52:53], v0, off
	s_waitcnt vmcnt(11)
	v_lshlrev_b32_e32 v0, 16, v132
	v_fmac_f32_e32 v55, v87, v0
	v_mul_f32_e32 v0, v55, v55
	v_fmamk_f32 v0, v0, 0xbdd2d3e8, v196
	v_mul_f32_e32 v0, v55, v0
	v_exp_f32_e32 v0, v0
	v_lshl_add_u64 v[52:53], v[56:57], 0, s[0:1]
	v_lshlrev_b64 v[52:53], 10, v[52:53]
	v_lshl_add_u64 v[52:53], v[92:93], 0, v[52:53]
	v_add_f32_e32 v0, 1.0, v0
	v_rcp_f32_e32 v0, v0
	s_nop 0
	v_mul_f32_e32 v0, v55, v0
	v_bfe_u32 v54, v0, 16, 1
	v_add3_u32 v0, v0, v54, s80
	global_store_short_d16_hi v[52:53], v0, off
	s_cbranch_scc0 .LBB0_149
	s_add_i32 s9, s9, s33
	s_xor_b32 s9, s9, 63
	s_cmpk_gt_i32 s9, 0xfff
	s_cbranch_scc0 .LBB0_141
